# weight conversion spread over all six non-prompt waves (was four) for more HBM bytes in flight; on top of MFMA-head trim
# speedup vs baseline: 1.0037x; 1.0026x over previous
; #define LAS __attribute__((address_space(3)))
; __device__ __forceinline__ ConvItem conv_decode(const Args& a, int it) {
;     unsigned char* ws = a.ws; const float* W; bf16_t* WT; int K, N, mode = 0;
;     if (it < 4 * 1024) { const int m = it >> 10; it &= 1023; const int jj = m >> 1; mode = 1 + (m & 1); W = a.in[15 + (m & 1)] + (size_t)jj * D * D; WT = (bf16_t*)(ws + WS_WSSM) + (size_t)jj * 4096 * D; K = D; N = D; }
;     else if ((it -= 4 * 1024) < 3072) { W = a.in[17]; WT = (bf16_t*)(ws + WS_WQKV); K = D; N = 3 * D; }
;     else if ((it -= 3072) < 1024) { W = a.in[19]; WT = (bf16_t*)(ws + WS_WAO); K = D; N = D; }
;     else if ((it -= 1024) < 4096) { W = a.in[20]; WT = (bf16_t*)(ws + WS_WHIN); K = D; N = 4 * D; }
;     else if ((it -= 4096) < 1024) { W = a.in[23]; WT = (bf16_t*)(ws + WS_WHO); K = D; N = D; }
;     else if ((it -= 1024) < 4 * 4096) { const int l = it >> 12; it &= 4095; W = a.in[28] + (size_t)l * D * FF; WT = (bf16_t*)(ws + WS_WF1) + (size_t)l * FF * D; K = D; N = FF; }
;     else { it -= 4 * 4096; const int l = it >> 12; it &= 4095; W = a.in[29] + (size_t)l * FF * D; WT = (bf16_t*)(ws + WS_WF2) + (size_t)l * D * FF; K = FF; N = D; }
; __device__ __forceinline__ void conv_worker(const Args& a, LAS float* scr, int w, int nw, int lane) {
;     f32x4 va[16], vb[16];
;     int it = w; if (it >= CONV_ITEMS) return;
;     ConvItem ca = conv_decode(a, it), cb = ca; conv_load(ca, va, lane);
;     for (;;) {
;         const bool hb = it + nw < CONV_ITEMS; if (hb) { cb = conv_decode(a, it + nw); conv_load(cb, vb, lane); }
; template <bool CONV> __device__ __forceinline__ void ph_ssm(const Args& a, LAS unsigned char* lds, int j, int L, int nblk, int b) {
;     ...
;         if (CONV && (wave & 2)) conv_worker(a, (LAS float*)wl, b * 4 + (wave & 1) + ((wave >> 2) << 1), nblk * 4, lane); }
.LBB0_123:
	s_mul_i32 s2, s90, 6
	s_add_i32 s2, s2, s39
	s_add_i32 s53, s2, -2
	s_cmp_gt_i32 s53, 0xb3ff
	s_cbranch_scc1 .LBB0_277
	s_cmpk_gt_i32 s53, 0xfff
	s_cbranch_scc0 .LBB0_132
	s_cmpk_gt_u32 s53, 0x1bff
	s_cbranch_scc0 .LBB0_133
	s_cmpk_gt_u32 s53, 0x1fff
	s_cbranch_scc0 .LBB0_134
	s_cmpk_gt_u32 s53, 0x2fff
	s_cbranch_scc0 .LBB0_135
	s_cmpk_gt_u32 s53, 0x33ff
	s_cbranch_scc0 .LBB0_136
	s_cmpk_gt_u32 s53, 0x73ff
	s_cbranch_scc0 .LBB0_137
	s_load_dwordx2 s[2:3], s[86:87], 0xe8
	s_add_i32 s5, s53, 0xffff8c00
	s_lshr_b32 s4, s5, 12
	s_and_b32 s13, s5, 0xfff
	s_mov_b32 s5, 0
	s_lshl_b64 s[6:7], s[4:5], 26
	s_waitcnt lgkmcnt(0)
	s_add_u32 s10, s2, s6
	s_addc_u32 s11, s3, s7
	s_lshl_b64 s[2:3], s[4:5], 25
	s_add_u32 s2, s68, s2
	s_addc_u32 s3, s69, s3
	s_add_u32 s6, s2, 0xe900000
	s_addc_u32 s7, s3, 0
	s_mov_b64 s[2:3], 0
	s_branch .LBB0_138

; #define LAS __attribute__((address_space(3)))
; __device__ __forceinline__ ConvItem conv_decode(const Args& a, int it) {
;     ...
;     const int nb = N / 64, kb = it / nb, n0 = 64 * (it - kb * nb), k0 = 64 * kb;
;     const int row0 = mode == 0 ? n0 : 256 * (n0 >> 7) + 128 * (mode - 1) + (n0 & 127);
;     ConvItem c; c.src = W + (size_t)k0 * N + n0; c.dst = WT + ((size_t)(row0 >> 8) * (K / 64) + kb) * 16384; c.N = N; c.K = K; c.w0 = row0 & 255; c.adj = mode == 0; return c;
; __device__ __forceinline__ void conv_worker(const Args& a, LAS float* scr, int w, int nw, int lane) {
;     f32x4 va[16], vb[16];
;     int it = w; if (it >= CONV_ITEMS) return;
;     ConvItem ca = conv_decode(a, it), cb = ca; conv_load(ca, va, lane);
;     for (;;) {
;         const bool hb = it + nw < CONV_ITEMS; if (hb) { cb = conv_decode(a, it + nw); conv_load(cb, vb, lane); }
.LBB0_155:
	s_lshr_b32 s5, s12, 6
	v_cvt_f32_u32_e32 v2, s5
	v_cvt_f32_u32_e32 v3, s13
	s_mul_i32 s42, s89, 6
	v_lshrrev_b32_e32 v131, 4, v130
	v_rcp_iflag_f32_e32 v4, v2
	v_mov_b32_e32 v135, 0
	v_or_b32_e32 v133, 4, v131
	v_or_b32_e32 v146, 8, v131
	v_mul_f32_e32 v4, v3, v4
	v_trunc_f32_e32 v4, v4
	v_cvt_u32_f32_e32 v5, v4
	v_fma_f32 v3, -v4, v2, v3
	v_cmp_ge_f32_e64 s[14:15], |v3|, v2
	s_cmp_lg_u64 s[14:15], 0
	v_readfirstlane_b32 s2, v5
	s_addc_u32 s2, s2, 0
	s_and_b32 s2, s2, 0xffff
	s_mul_i32 s5, s5, s2
	s_sub_i32 s5, s13, s5
	s_lshl_b32 s14, s5, 6
	s_lshl_b32 s5, s5, 7
	s_lshl_b32 s15, s4, 7
	s_and_b32 s5, s5, 0xffffff00
	s_and_b32 s13, s14, 64
	s_add_i32 s15, s15, s5
	s_or_b32 s5, s15, s13
	s_add_i32 s13, s5, 0xffffff80
	s_cmp_eq_u32 s4, 0
	s_cselect_b64 s[4:5], -1, 0
	v_cndmask_b32_e64 v175, 0, 1, s[4:5]
	s_and_b64 s[4:5], s[4:5], exec
	s_cselect_b32 s13, s14, s13
	s_lshl_b32 s4, s2, 6
	s_mul_hi_u32 s5, s4, s12
	s_mul_i32 s4, s4, s12
	s_lshl_b64 s[4:5], s[4:5], 2
	s_waitcnt lgkmcnt(0)
; #define LAS __attribute__((address_space(3)))
; __device__ __forceinline__ void conv_load(const ConvItem& c, f32x4 (&wv)[16], int lane) {
; #pragma unroll
;     for (int i = 0; i < 16; ++i) wv[i] = __builtin_nontemporal_load((const f32x4*)(c.src + (size_t)(4 * i + (lane >> 4)) * c.N + 4 * (lane & 15)));
; }
; __device__ __forceinline__ void conv_store(const ConvItem& c, const f32x4 (&wv)[16], LAS float* scr, int lane) {
; #pragma unroll
;     for (int i = 0; i < 16; ++i) { LAS float* d = scr + (4 * i + (lane >> 4)) * 65 + 4 * (lane & 15); d[0] = wv[i][0]; d[1] = wv[i][1]; d[2] = wv[i][2]; d[3] = wv[i][3]; }
; __device__ __forceinline__ void conv_worker(const Args& a, LAS float* scr, int w, int nw, int lane) {
;     f32x4 va[16], vb[16];
;     int it = w; if (it >= CONV_ITEMS) return;
;     ConvItem ca = conv_decode(a, it), cb = ca; conv_load(ca, va, lane);
;     for (;;) {
;         const bool hb = it + nw < CONV_ITEMS; if (hb) { cb = conv_decode(a, it + nw); conv_load(cb, vb, lane); }
;         conv_store(ca, va, scr, lane); if (!hb) break; it += nw;
;         const bool ha = it + nw < CONV_ITEMS; if (ha) { ca = conv_decode(a, it + nw); conv_load(ca, va, lane); }
;         conv_store(cb, vb, scr, lane); if (!ha) break; it += nw;
;     }
; }
	s_add_u32 s10, s10, s4
	s_addc_u32 s11, s11, s5
	s_ashr_i32 s15, s14, 31
	s_lshl_b64 s[4:5], s[14:15], 2
	v_lshlrev_b32_e32 v2, 2, v130
	s_add_u32 s10, s10, s4
	v_and_b32_e32 v132, 60, v2
	v_mul_u32_u24_e32 v2, s12, v131
	s_addc_u32 s11, s11, s5
	v_lshlrev_b32_e32 v134, 2, v2
	v_lshl_add_u64 v[2:3], s[10:11], 0, v[134:135]
	v_lshlrev_b32_e32 v134, 2, v132
	v_lshl_add_u64 v[10:11], v[2:3], 0, v[134:135]
	v_mul_u32_u24_e32 v2, s12, v133
	v_lshlrev_b32_e32 v2, 2, v2
	v_mov_b32_e32 v3, v135
	v_lshl_add_u64 v[2:3], s[10:11], 0, v[2:3]
	v_lshl_add_u64 v[12:13], v[2:3], 0, v[134:135]
	global_load_dwordx4 v[2:5], v[10:11], off nt
	global_load_dwordx4 v[6:9], v[12:13], off nt
	v_mul_u32_u24_e32 v10, s12, v146
	v_lshlrev_b32_e32 v10, 2, v10
	v_mov_b32_e32 v11, v135
	v_lshl_add_u64 v[10:11], s[10:11], 0, v[10:11]
	v_or_b32_e32 v147, 12, v131
	v_lshl_add_u64 v[18:19], v[10:11], 0, v[134:135]
	v_mul_u32_u24_e32 v10, s12, v147
	v_lshlrev_b32_e32 v10, 2, v10
	v_mov_b32_e32 v11, v135
	v_lshl_add_u64 v[10:11], s[10:11], 0, v[10:11]
	v_or_b32_e32 v148, 16, v131
	v_lshl_add_u64 v[20:21], v[10:11], 0, v[134:135]
	global_load_dwordx4 v[10:13], v[18:19], off nt
	global_load_dwordx4 v[14:17], v[20:21], off nt
	v_mul_u32_u24_e32 v18, s12, v148
	v_lshlrev_b32_e32 v18, 2, v18
	v_mov_b32_e32 v19, v135
	v_lshl_add_u64 v[18:19], s[10:11], 0, v[18:19]
	v_or_b32_e32 v149, 20, v131
	v_lshl_add_u64 v[26:27], v[18:19], 0, v[134:135]
	v_mul_u32_u24_e32 v18, s12, v149
	v_lshlrev_b32_e32 v18, 2, v18
	v_mov_b32_e32 v19, v135
	v_lshl_add_u64 v[18:19], s[10:11], 0, v[18:19]
	v_or_b32_e32 v150, 24, v131
	v_lshl_add_u64 v[28:29], v[18:19], 0, v[134:135]
	global_load_dwordx4 v[18:21], v[26:27], off nt
	global_load_dwordx4 v[22:25], v[28:29], off nt
	v_mul_u32_u24_e32 v26, s12, v150
	v_lshlrev_b32_e32 v26, 2, v26
	v_mov_b32_e32 v27, v135
	v_lshl_add_u64 v[26:27], s[10:11], 0, v[26:27]
	v_or_b32_e32 v151, 28, v131
	v_lshl_add_u64 v[34:35], v[26:27], 0, v[134:135]
	v_mul_u32_u24_e32 v26, s12, v151
	v_lshlrev_b32_e32 v26, 2, v26
	v_mov_b32_e32 v27, v135
	v_lshl_add_u64 v[26:27], s[10:11], 0, v[26:27]
	v_or_b32_e32 v152, 32, v131
	v_lshl_add_u64 v[36:37], v[26:27], 0, v[134:135]
	global_load_dwordx4 v[26:29], v[34:35], off nt
	global_load_dwordx4 v[30:33], v[36:37], off nt
	v_mul_u32_u24_e32 v34, s12, v152
	v_lshlrev_b32_e32 v34, 2, v34
	v_mov_b32_e32 v35, v135
	v_lshl_add_u64 v[34:35], s[10:11], 0, v[34:35]
	v_or_b32_e32 v153, 36, v131
	v_lshl_add_u64 v[42:43], v[34:35], 0, v[134:135]
	v_mul_u32_u24_e32 v34, s12, v153
	v_lshlrev_b32_e32 v34, 2, v34
	v_mov_b32_e32 v35, v135
	v_lshl_add_u64 v[34:35], s[10:11], 0, v[34:35]
	v_or_b32_e32 v154, 40, v131
	v_lshl_add_u64 v[44:45], v[34:35], 0, v[134:135]
	global_load_dwordx4 v[34:37], v[42:43], off nt
	global_load_dwordx4 v[38:41], v[44:45], off nt
	v_mul_u32_u24_e32 v42, s12, v154
	v_lshlrev_b32_e32 v42, 2, v42
	v_mov_b32_e32 v43, v135
	v_lshl_add_u64 v[42:43], s[10:11], 0, v[42:43]
	v_or_b32_e32 v155, 44, v131
	v_lshl_add_u64 v[50:51], v[42:43], 0, v[134:135]
	v_mul_u32_u24_e32 v42, s12, v155
	v_lshlrev_b32_e32 v42, 2, v42
	v_mov_b32_e32 v43, v135
	v_lshl_add_u64 v[42:43], s[10:11], 0, v[42:43]
	v_or_b32_e32 v156, 48, v131
	v_lshl_add_u64 v[52:53], v[42:43], 0, v[134:135]
	global_load_dwordx4 v[42:45], v[50:51], off nt
	global_load_dwordx4 v[46:49], v[52:53], off nt
	v_mul_u32_u24_e32 v50, s12, v156
	v_lshlrev_b32_e32 v50, 2, v50
	v_mov_b32_e32 v51, v135
	v_lshl_add_u64 v[50:51], s[10:11], 0, v[50:51]
	v_or_b32_e32 v157, 52, v131
	v_lshl_add_u64 v[58:59], v[50:51], 0, v[134:135]
	v_mul_u32_u24_e32 v50, s12, v157
	v_lshlrev_b32_e32 v50, 2, v50
	v_mov_b32_e32 v51, v135
	v_lshl_add_u64 v[50:51], s[10:11], 0, v[50:51]
	v_or_b32_e32 v158, 56, v131
	v_lshl_add_u64 v[60:61], v[50:51], 0, v[134:135]
	global_load_dwordx4 v[50:53], v[58:59], off nt
	global_load_dwordx4 v[54:57], v[60:61], off nt
	v_mul_u32_u24_e32 v58, s12, v158
	v_or_b32_e32 v159, 60, v131
	v_lshlrev_b32_e32 v58, 2, v58
	v_mov_b32_e32 v59, v135
	v_mul_u32_u24_e32 v60, s12, v159
	v_lshl_add_u64 v[58:59], s[10:11], 0, v[58:59]
	v_lshlrev_b32_e32 v60, 2, v60
	v_mov_b32_e32 v61, v135
	v_lshl_add_u64 v[58:59], v[58:59], 0, v[134:135]
	v_lshl_add_u64 v[60:61], s[10:11], 0, v[60:61]
	v_lshl_add_u64 v[60:61], v[60:61], 0, v[134:135]
	global_load_dwordx4 v[74:77], v[58:59], off nt
	global_load_dwordx4 v[78:81], v[60:61], off nt
	s_ashr_i32 s4, s13, 8
	s_ashr_i32 s5, s4, 31
	s_mul_i32 s5, s8, s5
	s_mul_hi_u32 s10, s8, s4
	s_add_i32 s5, s10, s5
	s_mul_i32 s9, s9, s4
	s_add_i32 s5, s5, s9
	s_mul_i32 s4, s8, s4
	s_add_u32 s4, s4, s2
	s_addc_u32 s5, s5, 0
	s_lshl_b64 s[4:5], s[4:5], 15
	s_add_u32 s30, s6, s4
	s_addc_u32 s31, s7, s5
	s_and_b32 s52, s13, 0xc0
	s_add_u32 s43, s68, 0xe900000
	s_addc_u32 s44, s69, 0
	s_add_u32 s45, s68, 0x6900000
	s_addc_u32 s46, s69, 0
	s_add_u32 s22, s68, 0x6100000
	s_addc_u32 s23, s69, 0
	s_add_u32 s24, s68, 0x4100000
	s_load_dwordx2 s[10:11], s[86:87], 0x88
	s_load_dwordx4 s[12:15], s[86:87], 0x98
	s_load_dwordx4 s[16:19], s[86:87], 0xe0
	s_load_dwordx2 s[20:21], s[86:87], 0xb8
	s_addc_u32 s25, s69, 0
	s_add_u32 s26, s68, 0x3900000
	s_addc_u32 s27, s69, 0
	v_lshlrev_b32_e32 v58, 3, v130
	s_add_u32 s28, s68, 0x2100000
	v_lshrrev_b32_e32 v160, 3, v130
	v_and_b32_e32 v58, 56, v58
	s_addc_u32 s29, s69, 0
	v_add_u32_e32 v59, s33, v134
	v_mul_u32_u24_e32 v60, 0x104, v131
	v_mul_u32_u24_e32 v61, 0x104, v58
	v_lshlrev_b32_e32 v161, 2, v160
	s_add_u32 s47, s68, 0x100000
	v_add3_u32 v162, s33, v61, v161
	v_or_b32_e32 v163, 32, v160
	v_or_b32_e32 v164, 40, v160
	v_or_b32_e32 v165, 48, v160
	v_or_b32_e32 v166, 56, v160
	v_and_b32_e32 v167, 16, v161
	v_bitop3_b32 v168, v161, 19, v160 bitop3:0xc8
	s_addc_u32 s48, s69, 0
	s_mul_i32 s49, s89, 12
	s_movk_i32 s50, 0x43
	v_lshlrev_b32_e32 v136, 1, v58
	s_movk_i32 s51, 0x63
	v_add_u32_e32 v169, v59, v60
	v_mov_b32_e32 v170, 0x43
	v_mov_b32_e32 v171, 0x100
	v_mov_b32_e32 v172, 0x200
	v_mov_b32_e32 v173, 0x300
	v_mov_b32_e32 v174, 0x63
	s_mov_b32 s40, s52
	s_mov_b64 s[34:35], s[30:31]
	v_mov_b32_e32 v176, v175
	s_branch .LBB0_157
